# samp_b: 31 conv weight loads issued as one batch instead of 16 serialized round trips (on top of h1/h3 LDS batching)
# speedup vs baseline: 1.0112x; 1.0027x over previous
.LBB0_612:
	s_or_b64 exec, exec, s[36:37]
	v_add_u32_e32 v0, v166, v163
	s_waitcnt vmcnt(3)
	ds_write_b16 v0, v152
	s_waitcnt vmcnt(2)
	ds_write_b16 v184, v145
	s_waitcnt lgkmcnt(0)
	s_barrier
	global_load_dword v198, v[66:67], off
	global_load_dword v199, v[68:69], off
	global_load_dword v200, v[70:71], off
	global_load_dword v201, v[72:73], off
	global_load_dword v202, v[74:75], off
	global_load_dword v203, v[76:77], off
	global_load_dword v204, v[78:79], off
	global_load_dword v205, v[84:85], off
	global_load_dword v206, v[86:87], off
	global_load_dword v207, v[88:89], off
	global_load_dword v216, v[90:91], off
	global_load_dword v217, v[92:93], off
	global_load_dword v218, v[94:95], off
	global_load_dword v219, v[96:97], off
	global_load_dword v220, v[98:99], off
	global_load_dword v221, v[100:101], off
	global_load_dword v223, v[102:103], off
	global_load_dword v224, v[104:105], off
	global_load_dword v225, v[106:107], off
	global_load_dword v229, v[108:109], off
	global_load_dword v230, v[110:111], off
	global_load_dword v232, v[112:113], off
	global_load_dword v239, v[114:115], off
	global_load_dword v240, v[116:117], off
	global_load_dword v241, v[118:119], off
	global_load_dword v242, v[120:121], off
	global_load_dword v243, v[122:123], off
	global_load_dword v244, v[124:125], off
	global_load_dword v245, v[126:127], off
	global_load_dword v246, v[128:129], off
	global_load_dword v247, v[130:131], off
	v_add_u32_e32 v0, s89, v157
	v_lshl_add_u32 v3, v0, 10, v53
	ds_read2st64_b32 v[210:211], v3 offset1:4
	ds_read2st64_b32 v[248:249], v3 offset0:8 offset1:12
	ds_read_b32 v195, v3 offset:30720
	s_waitcnt vmcnt(0)
	s_waitcnt lgkmcnt(2)
	v_fmac_f32_e32 v143, v198, v210
	v_fmac_f32_e32 v143, v199, v211
	ds_read2st64_b32 v[210:211], v3 offset0:16 offset1:20
	s_waitcnt lgkmcnt(2)
	v_fmac_f32_e32 v143, v200, v248
	v_fmac_f32_e32 v143, v201, v249
	ds_read2st64_b32 v[248:249], v3 offset0:24 offset1:28
	s_waitcnt lgkmcnt(1)
	v_fmac_f32_e32 v143, v202, v210
	v_fmac_f32_e32 v143, v203, v211
	ds_read2st64_b32 v[210:211], v3 offset0:32 offset1:36
	s_waitcnt lgkmcnt(1)
	v_fmac_f32_e32 v143, v204, v248
	v_fmac_f32_e32 v143, v205, v249
	ds_read2st64_b32 v[248:249], v3 offset0:40 offset1:44
	s_waitcnt lgkmcnt(1)
	v_fmac_f32_e32 v143, v206, v210
	v_fmac_f32_e32 v143, v207, v211
	ds_read2st64_b32 v[210:211], v3 offset0:48 offset1:52
	s_waitcnt lgkmcnt(1)
	v_fmac_f32_e32 v143, v216, v248
	v_fmac_f32_e32 v143, v217, v249
	ds_read2st64_b32 v[248:249], v3 offset0:56 offset1:60
	s_waitcnt lgkmcnt(1)
	v_fmac_f32_e32 v143, v218, v210
	v_fmac_f32_e32 v143, v219, v211
	ds_read2st64_b32 v[210:211], v3 offset0:64 offset1:68
	s_waitcnt lgkmcnt(1)
	v_fmac_f32_e32 v143, v220, v248
	v_fmac_f32_e32 v143, v221, v249
	ds_read2st64_b32 v[248:249], v3 offset0:72 offset1:76
	s_waitcnt lgkmcnt(1)
	v_fmac_f32_e32 v143, v223, v210
	v_fmac_f32_e32 v143, v224, v211
	ds_read2st64_b32 v[210:211], v3 offset0:80 offset1:84
	s_waitcnt lgkmcnt(1)
	v_fmac_f32_e32 v143, v225, v248
	v_fmac_f32_e32 v143, v229, v249
	ds_read2st64_b32 v[248:249], v3 offset0:88 offset1:92
	s_waitcnt lgkmcnt(1)
	v_fmac_f32_e32 v143, v230, v210
	v_fmac_f32_e32 v143, v232, v211
	ds_read2st64_b32 v[210:211], v3 offset0:96 offset1:100
	s_waitcnt lgkmcnt(1)
	v_fmac_f32_e32 v143, v239, v248
	v_fmac_f32_e32 v143, v240, v249
	ds_read2st64_b32 v[248:249], v3 offset0:104 offset1:108
	s_waitcnt lgkmcnt(1)
	v_fmac_f32_e32 v143, v241, v210
	v_fmac_f32_e32 v143, v242, v211
	ds_read2st64_b32 v[210:211], v3 offset0:112 offset1:116
	s_waitcnt lgkmcnt(1)
	v_fmac_f32_e32 v143, v243, v248
	v_fmac_f32_e32 v143, v244, v249
	s_waitcnt lgkmcnt(0)
	v_fmac_f32_e32 v143, v245, v210
	v_fmac_f32_e32 v143, v246, v211
	s_waitcnt lgkmcnt(0)
	v_fmac_f32_e32 v143, v247, v195
	ds_write_b32 v3, v143 offset:34816
	s_and_saveexec_b64 s[36:37], s[18:19]
	s_cbranch_execz .LBB0_615
	s_add_u32 s34, s83, s34
	s_addc_u32 s35, s84, s35
	s_mul_i32 s38, s71, 0x3c00
	s_add_u32 s34, s34, s38
	v_cndmask_b32_e64 v0, 0, 1, s[64:65]
	s_movk_i32 s38, 0x3c00
	v_mul_lo_u32 v0, v0, s38
	s_addc_u32 s35, s35, 0
	v_add_u32_e32 v2, v155, v0
	s_mov_b64 s[38:39], 0
	v_mov_b32_e32 v0, v54
	v_mov_b32_e32 v3, v177
